# v10
# baseline (speedup 1.0000x reference)
; #define STAGE(P_, BASE, br, kt) do { const char* _gb = (const char*)(BASE) + (((long)(br) * K + (long)(kt) * BK) << 1); \
;     const unsigned _ld = (unsigned)(uintptr_t)(P_) + wv1024; \
;     glds16(voff0, _gb, _ld); glds16(voff1, _gb, _ld + 8192u); } while (0)
; #define LDA(dst, b, h) for (int m = 0; m < 4; ++m) for (int k = 0; k < 2; ++k) \
;     dst[m][k] = *reinterpret_cast<const bf16x8*>((char*)SA(b, h) + lds_byte(wr * 64 + m * 16 + fr, k * 32 + fq * 8))
; #define LDB(dst, b, h) for (int n = 0; n < 2; ++n) for (int k = 0; k < 2; ++k) \
;     dst[n][k] = *reinterpret_cast<const bf16x8*>((char*)SB(b, h) + lds_byte(wc * 32 + n * 16 + fr, k * 32 + fq * 8))
; #define MMA(ai, bj, At_, Bt_) do { __builtin_amdgcn_s_setprio(1); \
;     for (int m = 0; m < 4; ++m) for (int n = 0; n < 2; ++n) for (int k = 0; k < 2; ++k) \
;       acc[ai][bj][m][n] = __builtin_amdgcn_mfma_f32_16x16x32_bf16(At_[m][k], Bt_[n][k], acc[ai][bj][m][n], 0, 0, 0); \
;     __builtin_amdgcn_s_setprio(0); } while (0)
; #define WAIT_V(n) asm volatile("s_waitcnt vmcnt(" #n ")" ::: "memory")
; #define WAIT_L(n) asm volatile("s_waitcnt lgkmcnt(" #n ")" ::: "memory")
; #define BAR __builtin_amdgcn_s_barrier()
; #define SCHED __builtin_amdgcn_sched_barrier(0)
; __device__ __forceinline__ void gemm_kloop(const u16* __restrict__ A, const u16* __restrict__ Bt, const int K,
;                                            const int brow, const int bcol, f32x4 (&acc)[2][2][4][2], u16* shm, const int tidk,
;                                            const bool first) {
;     ...
;   for (int t = 0; t < nt - 2; t += 2) {
;     LDB(B0, 0, 0); SCHED; LDA(At, 0, 0); STAGE(SA(1, 1), A, brow + HALF, t + 1);
;     WAIT_L(8); BAR; WAIT_L(0); MMA(0, 0, At, B0); BAR; SCHED;
;     LDB(B1, 0, 1); STAGE(SB(0, 0), Bt, bcol, t + 2);
;     BAR; WAIT_L(0); MMA(0, 1, At, B1); BAR;
;     LDA(At, 0, 1); STAGE(SA(0, 0), A, brow, t + 2);
;     BAR; WAIT_L(0); MMA(1, 0, At, B0); BAR; SCHED;
;     STAGE(SB(0, 1), Bt, bcol + HALF, t + 2);
;     WAIT_V(6); BAR; MMA(1, 1, At, B1); BAR;
;     LDB(B0, 1, 0); SCHED; LDA(At, 1, 0); STAGE(SA(0, 1), A, brow + HALF, t + 2);
;     WAIT_L(8); BAR; WAIT_L(0); MMA(0, 0, At, B0); BAR; SCHED;
.LBB0_153:
	ds_read_b128 v[130:133], v209
	ds_read_b128 v[134:137], v209 offset:1024
	ds_read_b128 v[138:141], v209 offset:2048
	ds_read_b128 v[142:145], v209 offset:3072
	ds_read_b128 v[146:149], v210
	ds_read_b128 v[150:153], v210 offset:1024
	ds_read_b128 v[154:157], v211
	ds_read_b128 v[158:161], v211 offset:1024
	ds_read_b128 v[162:165], v212
	ds_read_b128 v[166:169], v212 offset:1024
	ds_read_b128 v[170:173], v213
	ds_read_b128 v[174:177], v213 offset:1024
	s_add_u32 s84, s73, s54
	s_addc_u32 s85, s52, s55
	s_add_u32 s84, s84, 0x80
	s_addc_u32 s85, s85, 0
	s_mov_b32 s8, m0
	s_mov_b32 m0, s69
	s_nop 0
	global_load_lds_dwordx4 v207, s[84:85]
	s_mov_b32 m0, s8
	s_nop 0
	s_mov_b32 s8, m0
	s_mov_b32 m0, s2
	s_nop 0
	global_load_lds_dwordx4 v208, s[84:85]
	s_mov_b32 m0, s8
	s_add_u32 s84, s15, s54
	s_addc_u32 s85, s58, s55
	s_mov_b32 s8, m0
	s_mov_b32 m0, s60
	s_nop 0
	global_load_lds_dwordx4 v207, s[84:85]
	s_mov_b32 m0, s8
	s_nop 0
	s_mov_b32 s8, m0
	s_mov_b32 m0, s57
	s_nop 0
	global_load_lds_dwordx4 v208, s[84:85]
	s_mov_b32 m0, s8
	s_waitcnt lgkmcnt(11)
	ds_read_b128 v[178:181], v214
	ds_read_b128 v[182:185], v214 offset:1024
	ds_read_b128 v[218:221], v214 offset:2048
	ds_read_b128 v[222:225], v214 offset:3072
	s_waitcnt lgkmcnt(4)
	s_barrier
	s_setprio 1
	v_mfma_f32_16x16x32_bf16 v[126:129], v[146:149], v[130:133], v[126:129]
	v_mfma_f32_16x16x32_bf16 v[122:125], v[146:149], v[138:141], v[122:125]
	v_mfma_f32_16x16x32_bf16 v[118:121], v[154:157], v[130:133], v[118:121]
	v_mfma_f32_16x16x32_bf16 v[114:117], v[154:157], v[138:141], v[114:117]
	v_mfma_f32_16x16x32_bf16 v[110:113], v[162:165], v[130:133], v[110:113]
	v_mfma_f32_16x16x32_bf16 v[106:109], v[162:165], v[138:141], v[106:109]
	v_mfma_f32_16x16x32_bf16 v[102:105], v[170:173], v[130:133], v[102:105]
	v_mfma_f32_16x16x32_bf16 v[98:101], v[170:173], v[138:141], v[98:101]
	v_mfma_f32_16x16x32_bf16 v[126:129], v[150:153], v[134:137], v[126:129]
	v_mfma_f32_16x16x32_bf16 v[122:125], v[150:153], v[142:145], v[122:125]
	v_mfma_f32_16x16x32_bf16 v[118:121], v[158:161], v[134:137], v[118:121]
	v_mfma_f32_16x16x32_bf16 v[114:117], v[158:161], v[142:145], v[114:117]
	v_mfma_f32_16x16x32_bf16 v[110:113], v[166:169], v[134:137], v[110:113]
	v_mfma_f32_16x16x32_bf16 v[106:109], v[166:169], v[142:145], v[106:109]
	v_mfma_f32_16x16x32_bf16 v[102:105], v[174:177], v[134:137], v[102:105]
	v_mfma_f32_16x16x32_bf16 v[98:101], v[174:177], v[142:145], v[98:101]
	s_waitcnt lgkmcnt(0)
	v_mfma_f32_16x16x32_bf16 v[94:97], v[146:149], v[178:181], v[94:97]
	v_mfma_f32_16x16x32_bf16 v[90:93], v[146:149], v[218:221], v[90:93]
	v_mfma_f32_16x16x32_bf16 v[86:89], v[154:157], v[178:181], v[86:89]
	v_mfma_f32_16x16x32_bf16 v[82:85], v[154:157], v[218:221], v[82:85]
	v_mfma_f32_16x16x32_bf16 v[78:81], v[162:165], v[178:181], v[78:81]
	v_mfma_f32_16x16x32_bf16 v[74:77], v[162:165], v[218:221], v[74:77]
	v_mfma_f32_16x16x32_bf16 v[70:73], v[170:173], v[178:181], v[70:73]
	v_mfma_f32_16x16x32_bf16 v[66:69], v[170:173], v[218:221], v[66:69]
	v_mfma_f32_16x16x32_bf16 v[94:97], v[150:153], v[182:185], v[94:97]
	v_mfma_f32_16x16x32_bf16 v[90:93], v[150:153], v[222:225], v[90:93]
	v_mfma_f32_16x16x32_bf16 v[86:89], v[158:161], v[182:185], v[86:89]
	v_mfma_f32_16x16x32_bf16 v[82:85], v[158:161], v[222:225], v[82:85]
	v_mfma_f32_16x16x32_bf16 v[78:81], v[166:169], v[182:185], v[78:81]
	v_mfma_f32_16x16x32_bf16 v[74:77], v[166:169], v[222:225], v[74:77]
	v_mfma_f32_16x16x32_bf16 v[70:73], v[174:177], v[182:185], v[70:73]
	v_mfma_f32_16x16x32_bf16 v[66:69], v[174:177], v[222:225], v[66:69]
	s_setprio 0
	s_barrier
	s_add_i32 s11, s11, 2
	ds_read_b128 v[146:149], v210 offset:16384
	ds_read_b128 v[150:153], v210 offset:17408
	ds_read_b128 v[154:157], v211 offset:16384
	ds_read_b128 v[158:161], v211 offset:17408
	ds_read_b128 v[162:165], v212 offset:16384
	ds_read_b128 v[166:169], v212 offset:17408
	ds_read_b128 v[170:173], v213 offset:16384
	ds_read_b128 v[174:177], v213 offset:17408
	s_add_u32 s84, s13, s54
	s_addc_u32 s85, s70, s55
	s_add_u32 s84, s84, 0x100
	s_addc_u32 s85, s85, 0
	s_mov_b32 s8, m0
	s_mov_b32 m0, s61
	s_nop 0
	global_load_lds_dwordx4 v207, s[84:85]
	s_mov_b32 m0, s8
	s_nop 0
	s_mov_b32 s8, m0
	s_mov_b32 m0, s66
	s_nop 0
	global_load_lds_dwordx4 v208, s[84:85]
	s_mov_b32 m0, s8
	s_add_u32 s84, s86, s54
	s_addc_u32 s85, s87, s55
	s_add_u32 s84, s84, 0x100
	s_addc_u32 s85, s85, 0
	s_mov_b32 s8, m0
	s_mov_b32 m0, s67
	s_nop 0
	global_load_lds_dwordx4 v207, s[84:85]
	s_mov_b32 m0, s8
	s_nop 0
	s_mov_b32 s8, m0
	s_mov_b32 m0, s78
	s_nop 0
	global_load_lds_dwordx4 v208, s[84:85]
	s_mov_b32 m0, s8
	s_waitcnt vmcnt(4)
	s_waitcnt lgkmcnt(0)
	s_barrier
; #define STAGE(P_, BASE, br, kt) do { const char* _gb = (const char*)(BASE) + (((long)(br) * K + (long)(kt) * BK) << 1); \
;     const unsigned _ld = (unsigned)(uintptr_t)(P_) + wv1024; \
;     glds16(voff0, _gb, _ld); glds16(voff1, _gb, _ld + 8192u); } while (0)
; #define LDA(dst, b, h) for (int m = 0; m < 4; ++m) for (int k = 0; k < 2; ++k) \
;     dst[m][k] = *reinterpret_cast<const bf16x8*>((char*)SA(b, h) + lds_byte(wr * 64 + m * 16 + fr, k * 32 + fq * 8))
; #define LDB(dst, b, h) for (int n = 0; n < 2; ++n) for (int k = 0; k < 2; ++k) \
;     dst[n][k] = *reinterpret_cast<const bf16x8*>((char*)SB(b, h) + lds_byte(wc * 32 + n * 16 + fr, k * 32 + fq * 8))
; #define MMA(ai, bj, At_, Bt_) do { __builtin_amdgcn_s_setprio(1); \
;     for (int m = 0; m < 4; ++m) for (int n = 0; n < 2; ++n) for (int k = 0; k < 2; ++k) \
;       acc[ai][bj][m][n] = __builtin_amdgcn_mfma_f32_16x16x32_bf16(At_[m][k], Bt_[n][k], acc[ai][bj][m][n], 0, 0, 0); \
;     __builtin_amdgcn_s_setprio(0); } while (0)
; #define WAIT_V(n) asm volatile("s_waitcnt vmcnt(" #n ")" ::: "memory")
; #define WAIT_L(n) asm volatile("s_waitcnt lgkmcnt(" #n ")" ::: "memory")
; #define BAR __builtin_amdgcn_s_barrier()
; #define SCHED __builtin_amdgcn_sched_barrier(0)
; __device__ __forceinline__ void gemm_kloop(const u16* __restrict__ A, const u16* __restrict__ Bt, const int K,
;                                            const int brow, const int bcol, f32x4 (&acc)[2][2][4][2], u16* shm, const int tidk,
;                                            const bool first) {
;     ...
;     WAIT_V(6); BAR; MMA(1, 1, At, B1); BAR;
;     LDB(B0, 1, 0); SCHED; LDA(At, 1, 0); STAGE(SA(0, 1), A, brow + HALF, t + 2);
;     WAIT_L(8); BAR; WAIT_L(0); MMA(0, 0, At, B0); BAR; SCHED;
;     LDB(B1, 1, 1); STAGE(SB(1, 0), Bt, bcol, t + 3);
;     BAR; WAIT_L(0); MMA(0, 1, At, B1); BAR;
;     LDA(At, 1, 1); STAGE(SA(1, 0), A, brow, t + 3);
;     BAR; WAIT_L(0); MMA(1, 0, At, B0); BAR; SCHED;
	s_setprio 1
	v_mfma_f32_16x16x32_bf16 v[62:65], v[146:149], v[130:133], v[62:65]
	v_mfma_f32_16x16x32_bf16 v[58:61], v[146:149], v[138:141], v[58:61]
	v_mfma_f32_16x16x32_bf16 v[54:57], v[154:157], v[130:133], v[54:57]
	v_mfma_f32_16x16x32_bf16 v[50:53], v[154:157], v[138:141], v[50:53]
	v_mfma_f32_16x16x32_bf16 v[46:49], v[162:165], v[130:133], v[46:49]
	v_mfma_f32_16x16x32_bf16 v[42:45], v[162:165], v[138:141], v[42:45]
	v_mfma_f32_16x16x32_bf16 v[38:41], v[170:173], v[130:133], v[38:41]
	v_mfma_f32_16x16x32_bf16 v[34:37], v[170:173], v[138:141], v[34:37]
	v_mfma_f32_16x16x32_bf16 v[62:65], v[150:153], v[134:137], v[62:65]
	v_mfma_f32_16x16x32_bf16 v[58:61], v[150:153], v[142:145], v[58:61]
	v_mfma_f32_16x16x32_bf16 v[54:57], v[158:161], v[134:137], v[54:57]
	v_mfma_f32_16x16x32_bf16 v[50:53], v[158:161], v[142:145], v[50:53]
	v_mfma_f32_16x16x32_bf16 v[46:49], v[166:169], v[134:137], v[46:49]
	v_mfma_f32_16x16x32_bf16 v[42:45], v[166:169], v[142:145], v[42:45]
	v_mfma_f32_16x16x32_bf16 v[38:41], v[174:177], v[134:137], v[38:41]
	v_mfma_f32_16x16x32_bf16 v[34:37], v[174:177], v[142:145], v[34:37]
	v_mfma_f32_16x16x32_bf16 v[30:33], v[146:149], v[178:181], v[30:33]
	v_mfma_f32_16x16x32_bf16 v[26:29], v[146:149], v[218:221], v[26:29]
	v_mfma_f32_16x16x32_bf16 v[22:25], v[154:157], v[178:181], v[22:25]
	v_mfma_f32_16x16x32_bf16 v[18:21], v[154:157], v[218:221], v[18:21]
	v_mfma_f32_16x16x32_bf16 v[14:17], v[162:165], v[178:181], v[14:17]
	v_mfma_f32_16x16x32_bf16 v[10:13], v[162:165], v[218:221], v[10:13]
	v_mfma_f32_16x16x32_bf16 v[6:9], v[170:173], v[178:181], v[6:9]
	v_mfma_f32_16x16x32_bf16 v[2:5], v[170:173], v[218:221], v[2:5]
	v_mfma_f32_16x16x32_bf16 v[30:33], v[150:153], v[182:185], v[30:33]
	v_mfma_f32_16x16x32_bf16 v[26:29], v[150:153], v[222:225], v[26:29]
	v_mfma_f32_16x16x32_bf16 v[22:25], v[158:161], v[182:185], v[22:25]
	v_mfma_f32_16x16x32_bf16 v[18:21], v[158:161], v[222:225], v[18:21]
	v_mfma_f32_16x16x32_bf16 v[14:17], v[166:169], v[182:185], v[14:17]
	v_mfma_f32_16x16x32_bf16 v[10:13], v[166:169], v[222:225], v[10:13]
	v_mfma_f32_16x16x32_bf16 v[6:9], v[174:177], v[182:185], v[6:9]
	v_mfma_f32_16x16x32_bf16 v[2:5], v[174:177], v[222:225], v[2:5]
	s_setprio 0
	s_barrier
	ds_read_b128 v[130:133], v215
	ds_read_b128 v[134:137], v215 offset:1024
	ds_read_b128 v[138:141], v215 offset:2048
	ds_read_b128 v[142:145], v215 offset:3072
	ds_read_b128 v[146:149], v210 offset:32768
	ds_read_b128 v[150:153], v210 offset:33792
	ds_read_b128 v[154:157], v211 offset:32768
	ds_read_b128 v[158:161], v211 offset:33792
	ds_read_b128 v[162:165], v212 offset:32768
	ds_read_b128 v[166:169], v212 offset:33792
	ds_read_b128 v[170:173], v213 offset:32768
	ds_read_b128 v[174:177], v213 offset:33792
	s_add_u32 s84, s73, s54
	s_addc_u32 s85, s52, s55
	s_add_u32 s84, s84, 0x100
	s_addc_u32 s85, s85, 0
	s_mov_b32 s8, m0
	s_mov_b32 m0, s88
	s_nop 0
	global_load_lds_dwordx4 v207, s[84:85]
	s_mov_b32 m0, s8
	s_nop 0
	s_mov_b32 s8, m0
	s_mov_b32 m0, s92
	s_nop 0
	global_load_lds_dwordx4 v208, s[84:85]
	s_mov_b32 m0, s8
	s_add_u32 s84, s71, s54
	s_addc_u32 s85, s3, s55
	s_mov_b32 s8, m0
	s_mov_b32 m0, s96
	s_nop 0
	global_load_lds_dwordx4 v207, s[84:85]
	s_mov_b32 m0, s8
	s_nop 0
	s_mov_b32 s8, m0
	s_mov_b32 m0, s97
	s_nop 0
	global_load_lds_dwordx4 v208, s[84:85]
	s_mov_b32 m0, s8
	s_waitcnt lgkmcnt(11)
	ds_read_b128 v[178:181], v216
	ds_read_b128 v[182:185], v216 offset:1024
	ds_read_b128 v[218:221], v216 offset:2048
	ds_read_b128 v[222:225], v216 offset:3072
	s_waitcnt lgkmcnt(4)
	s_barrier
	s_setprio 1
	v_mfma_f32_16x16x32_bf16 v[126:129], v[146:149], v[130:133], v[126:129]
	v_mfma_f32_16x16x32_bf16 v[122:125], v[146:149], v[138:141], v[122:125]
	v_mfma_f32_16x16x32_bf16 v[118:121], v[154:157], v[130:133], v[118:121]
	v_mfma_f32_16x16x32_bf16 v[114:117], v[154:157], v[138:141], v[114:117]
	v_mfma_f32_16x16x32_bf16 v[110:113], v[162:165], v[130:133], v[110:113]
	v_mfma_f32_16x16x32_bf16 v[106:109], v[162:165], v[138:141], v[106:109]
	v_mfma_f32_16x16x32_bf16 v[102:105], v[170:173], v[130:133], v[102:105]
	v_mfma_f32_16x16x32_bf16 v[98:101], v[170:173], v[138:141], v[98:101]
	v_mfma_f32_16x16x32_bf16 v[126:129], v[150:153], v[134:137], v[126:129]
	v_mfma_f32_16x16x32_bf16 v[122:125], v[150:153], v[142:145], v[122:125]
	v_mfma_f32_16x16x32_bf16 v[118:121], v[158:161], v[134:137], v[118:121]
	v_mfma_f32_16x16x32_bf16 v[114:117], v[158:161], v[142:145], v[114:117]
	v_mfma_f32_16x16x32_bf16 v[110:113], v[166:169], v[134:137], v[110:113]
	v_mfma_f32_16x16x32_bf16 v[106:109], v[166:169], v[142:145], v[106:109]
	v_mfma_f32_16x16x32_bf16 v[102:105], v[174:177], v[134:137], v[102:105]
	v_mfma_f32_16x16x32_bf16 v[98:101], v[174:177], v[142:145], v[98:101]
	s_waitcnt lgkmcnt(0)
	v_mfma_f32_16x16x32_bf16 v[94:97], v[146:149], v[178:181], v[94:97]
	v_mfma_f32_16x16x32_bf16 v[90:93], v[146:149], v[218:221], v[90:93]
	v_mfma_f32_16x16x32_bf16 v[86:89], v[154:157], v[178:181], v[86:89]
	v_mfma_f32_16x16x32_bf16 v[82:85], v[154:157], v[218:221], v[82:85]
	v_mfma_f32_16x16x32_bf16 v[78:81], v[162:165], v[178:181], v[78:81]
	v_mfma_f32_16x16x32_bf16 v[74:77], v[162:165], v[218:221], v[74:77]
	v_mfma_f32_16x16x32_bf16 v[70:73], v[170:173], v[178:181], v[70:73]
	v_mfma_f32_16x16x32_bf16 v[66:69], v[170:173], v[218:221], v[66:69]
	v_mfma_f32_16x16x32_bf16 v[94:97], v[150:153], v[182:185], v[94:97]
	v_mfma_f32_16x16x32_bf16 v[90:93], v[150:153], v[222:225], v[90:93]
	v_mfma_f32_16x16x32_bf16 v[86:89], v[158:161], v[182:185], v[86:89]
	v_mfma_f32_16x16x32_bf16 v[82:85], v[158:161], v[222:225], v[82:85]
	v_mfma_f32_16x16x32_bf16 v[78:81], v[166:169], v[182:185], v[78:81]
	v_mfma_f32_16x16x32_bf16 v[74:77], v[166:169], v[222:225], v[74:77]
	v_mfma_f32_16x16x32_bf16 v[70:73], v[174:177], v[182:185], v[70:73]
	v_mfma_f32_16x16x32_bf16 v[66:69], v[174:177], v[222:225], v[66:69]
	s_setprio 0
	s_barrier
; #define STAGE(P_, BASE, br, kt) do { const char* _gb = (const char*)(BASE) + (((long)(br) * K + (long)(kt) * BK) << 1); \
;     const unsigned _ld = (unsigned)(uintptr_t)(P_) + wv1024; \
;     glds16(voff0, _gb, _ld); glds16(voff1, _gb, _ld + 8192u); } while (0)
; #define LDA(dst, b, h) for (int m = 0; m < 4; ++m) for (int k = 0; k < 2; ++k) \
;     dst[m][k] = *reinterpret_cast<const bf16x8*>((char*)SA(b, h) + lds_byte(wr * 64 + m * 16 + fr, k * 32 + fq * 8))
; #define LDB(dst, b, h) for (int n = 0; n < 2; ++n) for (int k = 0; k < 2; ++k) \
;     dst[n][k] = *reinterpret_cast<const bf16x8*>((char*)SB(b, h) + lds_byte(wc * 32 + n * 16 + fr, k * 32 + fq * 8))
; #define MMA(ai, bj, At_, Bt_) do { __builtin_amdgcn_s_setprio(1); \
;     for (int m = 0; m < 4; ++m) for (int n = 0; n < 2; ++n) for (int k = 0; k < 2; ++k) \
;       acc[ai][bj][m][n] = __builtin_amdgcn_mfma_f32_16x16x32_bf16(At_[m][k], Bt_[n][k], acc[ai][bj][m][n], 0, 0, 0); \
;     __builtin_amdgcn_s_setprio(0); } while (0)
; #define WAIT_V(n) asm volatile("s_waitcnt vmcnt(" #n ")" ::: "memory")
; #define WAIT_L(n) asm volatile("s_waitcnt lgkmcnt(" #n ")" ::: "memory")
; #define BAR __builtin_amdgcn_s_barrier()
; #define SCHED __builtin_amdgcn_sched_barrier(0)
; __device__ __forceinline__ void gemm_kloop(const u16* __restrict__ A, const u16* __restrict__ Bt, const int K,
;                                            const int brow, const int bcol, f32x4 (&acc)[2][2][4][2], u16* shm, const int tidk,
;                                            const bool first) {
;     ...
;     LDA(At, 1, 1); STAGE(SA(1, 0), A, brow, t + 3);
;     BAR; WAIT_L(0); MMA(1, 0, At, B0); BAR; SCHED;
;     STAGE(SB(1, 1), Bt, bcol + HALF, t + 3);
;     WAIT_V(6); BAR; MMA(1, 1, At, B1); BAR;
;   }
;   { LDB(B0, 0, 0); LDA(At, 0, 0); STAGE(SA(1, 1), A, brow + HALF, nt - 1);
;     BAR; WAIT_L(0); MMA(0, 0, At, B0); BAR;
	ds_read_b128 v[146:149], v210 offset:49152
	ds_read_b128 v[150:153], v210 offset:50176
	ds_read_b128 v[154:157], v211 offset:49152
	ds_read_b128 v[158:161], v211 offset:50176
	ds_read_b128 v[162:165], v212 offset:49152
	ds_read_b128 v[166:169], v212 offset:50176
	ds_read_b128 v[170:173], v213 offset:49152
	ds_read_b128 v[174:177], v213 offset:50176
	s_add_u32 s84, s13, s54
	s_addc_u32 s85, s70, s55
	s_add_u32 s84, s84, 0x180
	s_addc_u32 s85, s85, 0
	s_mov_b32 s8, m0
	s_mov_b32 m0, s98
	s_nop 0
	global_load_lds_dwordx4 v207, s[84:85]
	s_mov_b32 m0, s8
	s_nop 0
	s_mov_b32 s8, m0
	s_mov_b32 m0, s99
	s_nop 0
	global_load_lds_dwordx4 v208, s[84:85]
	s_mov_b32 m0, s8
	s_add_u32 s84, s86, s54
	s_addc_u32 s85, s87, s55
	s_add_u32 s84, s84, 0x180
	s_addc_u32 s85, s85, 0
	s_mov_b32 s8, m0
	s_mov_b32 m0, vcc_lo
	s_nop 0
	global_load_lds_dwordx4 v207, s[84:85]
	s_mov_b32 m0, s8
	s_nop 0
	s_mov_b32 s8, m0
	s_mov_b32 m0, vcc_hi
	s_nop 0
	global_load_lds_dwordx4 v208, s[84:85]
	s_mov_b32 m0, s8
	s_waitcnt vmcnt(4)
	s_waitcnt lgkmcnt(0)
	s_barrier
	s_setprio 1
	v_mfma_f32_16x16x32_bf16 v[62:65], v[146:149], v[130:133], v[62:65]
	v_mfma_f32_16x16x32_bf16 v[58:61], v[146:149], v[138:141], v[58:61]
	v_mfma_f32_16x16x32_bf16 v[54:57], v[154:157], v[130:133], v[54:57]
	v_mfma_f32_16x16x32_bf16 v[50:53], v[154:157], v[138:141], v[50:53]
	v_mfma_f32_16x16x32_bf16 v[46:49], v[162:165], v[130:133], v[46:49]
	v_mfma_f32_16x16x32_bf16 v[42:45], v[162:165], v[138:141], v[42:45]
	v_mfma_f32_16x16x32_bf16 v[38:41], v[170:173], v[130:133], v[38:41]
	v_mfma_f32_16x16x32_bf16 v[34:37], v[170:173], v[138:141], v[34:37]
	v_mfma_f32_16x16x32_bf16 v[62:65], v[150:153], v[134:137], v[62:65]
	v_mfma_f32_16x16x32_bf16 v[58:61], v[150:153], v[142:145], v[58:61]
	v_mfma_f32_16x16x32_bf16 v[54:57], v[158:161], v[134:137], v[54:57]
	v_mfma_f32_16x16x32_bf16 v[50:53], v[158:161], v[142:145], v[50:53]
	v_mfma_f32_16x16x32_bf16 v[46:49], v[166:169], v[134:137], v[46:49]
	v_mfma_f32_16x16x32_bf16 v[42:45], v[166:169], v[142:145], v[42:45]
	v_mfma_f32_16x16x32_bf16 v[38:41], v[174:177], v[134:137], v[38:41]
	v_mfma_f32_16x16x32_bf16 v[34:37], v[174:177], v[142:145], v[34:37]
	v_mfma_f32_16x16x32_bf16 v[30:33], v[146:149], v[178:181], v[30:33]
	v_mfma_f32_16x16x32_bf16 v[26:29], v[146:149], v[218:221], v[26:29]
	v_mfma_f32_16x16x32_bf16 v[22:25], v[154:157], v[178:181], v[22:25]
	v_mfma_f32_16x16x32_bf16 v[18:21], v[154:157], v[218:221], v[18:21]
	v_mfma_f32_16x16x32_bf16 v[14:17], v[162:165], v[178:181], v[14:17]
	v_mfma_f32_16x16x32_bf16 v[10:13], v[162:165], v[218:221], v[10:13]
	v_mfma_f32_16x16x32_bf16 v[6:9], v[170:173], v[178:181], v[6:9]
	v_mfma_f32_16x16x32_bf16 v[2:5], v[170:173], v[218:221], v[2:5]
	v_mfma_f32_16x16x32_bf16 v[30:33], v[150:153], v[182:185], v[30:33]
	v_mfma_f32_16x16x32_bf16 v[26:29], v[150:153], v[222:225], v[26:29]
	v_mfma_f32_16x16x32_bf16 v[22:25], v[158:161], v[182:185], v[22:25]
	v_mfma_f32_16x16x32_bf16 v[18:21], v[158:161], v[222:225], v[18:21]
	v_mfma_f32_16x16x32_bf16 v[14:17], v[166:169], v[182:185], v[14:17]
	v_mfma_f32_16x16x32_bf16 v[10:13], v[166:169], v[222:225], v[10:13]
	v_mfma_f32_16x16x32_bf16 v[6:9], v[174:177], v[182:185], v[6:9]
	v_mfma_f32_16x16x32_bf16 v[2:5], v[174:177], v[222:225], v[2:5]
	s_setprio 0
	s_add_u32 s54, s54, 0x100
	s_addc_u32 s55, s55, 0
	s_cmp_lt_u32 s11, s64
	s_barrier
	s_cbranch_scc1 .LBB0_153
	s_add_u32 s84, s73, s54
	s_addc_u32 s85, s52, s55
	s_add_u32 s84, s84, 0x80
	s_addc_u32 s85, s85, 0
	s_mov_b32 s8, m0
	s_mov_b32 m0, s69
	s_nop 0
	global_load_lds_dwordx4 v207, s[84:85]
	s_mov_b32 m0, s8
	s_nop 0
	s_mov_b32 s8, m0
	s_mov_b32 m0, s2
	s_nop 0
	global_load_lds_dwordx4 v208, s[84:85]
	s_mov_b32 m0, s8
	ds_read_b128 v[130:133], v209
	ds_read_b128 v[134:137], v209 offset:1024
	ds_read_b128 v[138:141], v209 offset:2048
	ds_read_b128 v[142:145], v209 offset:3072
	ds_read_b128 v[146:149], v210
	ds_read_b128 v[150:153], v210 offset:1024
	ds_read_b128 v[154:157], v211
	ds_read_b128 v[158:161], v211 offset:1024
	ds_read_b128 v[162:165], v212
	ds_read_b128 v[166:169], v212 offset:1024
	ds_read_b128 v[170:173], v213
	ds_read_b128 v[174:177], v213 offset:1024
	s_mul_i32 s1, s56, s12
	v_readlane_b32 s2, v250, 49
	s_mul_hi_i32 s0, s56, s12
	s_add_u32 s2, s2, s1
	v_readlane_b32 s1, v250, 50
	s_addc_u32 s3, s1, s0
	s_mov_b32 s0, m0
	s_mov_b32 m0, s60
	s_nop 0
	global_load_lds_dwordx4 v207, s[2:3]
	s_mov_b32 m0, s0
	s_nop 0
	s_mov_b32 s0, m0
	s_mov_b32 m0, s57
	s_nop 0
	global_load_lds_dwordx4 v208, s[2:3]
	s_mov_b32 m0, s0
	s_barrier
	s_waitcnt lgkmcnt(0)
	s_setprio 1
	s_waitcnt lgkmcnt(7)
	v_mfma_f32_16x16x32_bf16 v[126:129], v[146:149], v[130:133], v[126:129]
	v_mfma_f32_16x16x32_bf16 v[122:125], v[146:149], v[138:141], v[122:125]
	s_waitcnt lgkmcnt(5)
	v_mfma_f32_16x16x32_bf16 v[118:121], v[154:157], v[130:133], v[118:121]
	s_waitcnt lgkmcnt(3)
	v_mfma_f32_16x16x32_bf16 v[110:113], v[162:165], v[130:133], v[110:113]
	v_mfma_f32_16x16x32_bf16 v[106:109], v[162:165], v[138:141], v[106:109]
	v_mfma_f32_16x16x32_bf16 v[126:129], v[150:153], v[134:137], v[126:129]
	v_mfma_f32_16x16x32_bf16 v[122:125], v[150:153], v[142:145], v[122:125]
	v_mfma_f32_16x16x32_bf16 v[118:121], v[158:161], v[134:137], v[118:121]
	v_mfma_f32_16x16x32_bf16 v[114:117], v[154:157], v[138:141], v[114:117]
	s_waitcnt lgkmcnt(2)
	v_mfma_f32_16x16x32_bf16 v[110:113], v[166:169], v[134:137], v[110:113]
	v_mfma_f32_16x16x32_bf16 v[106:109], v[166:169], v[142:145], v[106:109]
	s_waitcnt lgkmcnt(1)
	v_mfma_f32_16x16x32_bf16 v[102:105], v[170:173], v[130:133], v[102:105]
	v_mfma_f32_16x16x32_bf16 v[98:101], v[170:173], v[138:141], v[98:101]
	v_mfma_f32_16x16x32_bf16 v[178:181], v[158:161], v[142:145], v[114:117]
	s_waitcnt lgkmcnt(0)
	v_mfma_f32_16x16x32_bf16 v[182:185], v[174:177], v[134:137], v[102:105]
	v_mfma_f32_16x16x32_bf16 v[218:221], v[174:177], v[142:145], v[98:101]
	s_setprio 0
	s_barrier
; #define LDA(dst, b, h) for (int m = 0; m < 4; ++m) for (int k = 0; k < 2; ++k) \
;     dst[m][k] = *reinterpret_cast<const bf16x8*>((char*)SA(b, h) + lds_byte(wr * 64 + m * 16 + fr, k * 32 + fq * 8))
; #define LDB(dst, b, h) for (int n = 0; n < 2; ++n) for (int k = 0; k < 2; ++k) \
;     dst[n][k] = *reinterpret_cast<const bf16x8*>((char*)SB(b, h) + lds_byte(wc * 32 + n * 16 + fr, k * 32 + fq * 8))
; #define MMA(ai, bj, At_, Bt_) do { __builtin_amdgcn_s_setprio(1); \
;     for (int m = 0; m < 4; ++m) for (int n = 0; n < 2; ++n) for (int k = 0; k < 2; ++k) \
;       acc[ai][bj][m][n] = __builtin_amdgcn_mfma_f32_16x16x32_bf16(At_[m][k], Bt_[n][k], acc[ai][bj][m][n], 0, 0, 0); \
;     __builtin_amdgcn_s_setprio(0); } while (0)
; #define WAIT_V(n) asm volatile("s_waitcnt vmcnt(" #n ")" ::: "memory")
; #define WAIT_L(n) asm volatile("s_waitcnt lgkmcnt(" #n ")" ::: "memory")
; #define BAR __builtin_amdgcn_s_barrier()
; __device__ __forceinline__ void gemm_kloop(const u16* __restrict__ A, const u16* __restrict__ Bt, const int K,
;                                            const int brow, const int bcol, f32x4 (&acc)[2][2][4][2], u16* shm, const int tidk,
;                                            const bool first) {
;     ...
;     LDB(B1, 0, 1); BAR; WAIT_L(0); MMA(0, 1, At, B1); BAR;
;     LDA(At, 0, 1); WAIT_V(4); BAR; WAIT_L(0); MMA(1, 0, At, B0); MMA(1, 1, At, B1); BAR; }
;   { LDB(B0, 1, 0); LDA(At, 1, 0); WAIT_V(2); BAR; WAIT_L(0); MMA(0, 0, At, B0); BAR;
;     LDB(B1, 1, 1); WAIT_V(0); BAR; WAIT_L(0); MMA(0, 1, At, B1); BAR;
	s_nop 1
	ds_read_b128 v[98:101], v214
	ds_read_b128 v[102:105], v214 offset:1024
	ds_read_b128 v[114:117], v214 offset:2048
	ds_read_b128 v[222:225], v214 offset:3072
	s_barrier
	s_waitcnt lgkmcnt(0)
	s_setprio 1
	s_waitcnt lgkmcnt(3)
	v_mfma_f32_16x16x32_bf16 v[94:97], v[146:149], v[98:101], v[94:97]
	s_waitcnt lgkmcnt(1)
	v_mfma_f32_16x16x32_bf16 v[90:93], v[146:149], v[114:117], v[90:93]
	v_mfma_f32_16x16x32_bf16 v[78:81], v[162:165], v[98:101], v[78:81]
	v_mfma_f32_16x16x32_bf16 v[74:77], v[162:165], v[114:117], v[74:77]
	v_mfma_f32_16x16x32_bf16 v[70:73], v[170:173], v[98:101], v[70:73]
	v_mfma_f32_16x16x32_bf16 v[66:69], v[170:173], v[114:117], v[66:69]
	v_mfma_f32_16x16x32_bf16 v[94:97], v[150:153], v[102:105], v[94:97]
	s_waitcnt lgkmcnt(0)
	v_mfma_f32_16x16x32_bf16 v[90:93], v[150:153], v[222:225], v[90:93]
	v_mfma_f32_16x16x32_bf16 v[86:89], v[154:157], v[98:101], v[86:89]
	v_mfma_f32_16x16x32_bf16 v[82:85], v[154:157], v[114:117], v[82:85]
	v_mfma_f32_16x16x32_bf16 v[78:81], v[166:169], v[102:105], v[78:81]
	v_mfma_f32_16x16x32_bf16 v[74:77], v[166:169], v[222:225], v[74:77]
	v_mfma_f32_16x16x32_bf16 v[70:73], v[174:177], v[102:105], v[70:73]
	v_mfma_f32_16x16x32_bf16 v[66:69], v[174:177], v[222:225], v[66:69]
	v_mfma_f32_16x16x32_bf16 v[146:149], v[158:161], v[102:105], v[86:89]
	v_mfma_f32_16x16x32_bf16 v[150:153], v[158:161], v[222:225], v[82:85]
	s_setprio 0
	s_barrier
	s_nop 0
	ds_read_b128 v[82:85], v210 offset:16384
	ds_read_b128 v[86:89], v210 offset:17408
	ds_read_b128 v[154:157], v211 offset:16384
	ds_read_b128 v[158:161], v211 offset:17408
	ds_read_b128 v[162:165], v212 offset:16384
	ds_read_b128 v[166:169], v212 offset:17408
	ds_read_b128 v[170:173], v213 offset:16384
	ds_read_b128 v[174:177], v213 offset:17408
	s_waitcnt vmcnt(4)
	s_barrier
	s_waitcnt lgkmcnt(0)
	s_setprio 1
	s_waitcnt lgkmcnt(7)
	v_mfma_f32_16x16x32_bf16 v[62:65], v[82:85], v[130:133], v[62:65]
	v_mfma_f32_16x16x32_bf16 v[58:61], v[82:85], v[138:141], v[58:61]
	s_waitcnt lgkmcnt(5)
	v_mfma_f32_16x16x32_bf16 v[54:57], v[154:157], v[130:133], v[54:57]
	s_waitcnt lgkmcnt(3)
	v_mfma_f32_16x16x32_bf16 v[46:49], v[162:165], v[130:133], v[46:49]
	v_mfma_f32_16x16x32_bf16 v[42:45], v[162:165], v[138:141], v[42:45]
	v_mfma_f32_16x16x32_bf16 v[62:65], v[86:89], v[134:137], v[62:65]
	v_mfma_f32_16x16x32_bf16 v[58:61], v[86:89], v[142:145], v[58:61]
	v_mfma_f32_16x16x32_bf16 v[54:57], v[158:161], v[134:137], v[54:57]
	v_mfma_f32_16x16x32_bf16 v[50:53], v[154:157], v[138:141], v[50:53]
	s_waitcnt lgkmcnt(2)
	v_mfma_f32_16x16x32_bf16 v[46:49], v[166:169], v[134:137], v[46:49]
	v_mfma_f32_16x16x32_bf16 v[42:45], v[166:169], v[142:145], v[42:45]
	s_waitcnt lgkmcnt(1)
	v_mfma_f32_16x16x32_bf16 v[38:41], v[170:173], v[130:133], v[38:41]
	v_mfma_f32_16x16x32_bf16 v[34:37], v[170:173], v[138:141], v[34:37]
	v_mfma_f32_16x16x32_bf16 v[226:229], v[158:161], v[142:145], v[50:53]
	s_waitcnt lgkmcnt(0)
	v_mfma_f32_16x16x32_bf16 v[230:233], v[174:177], v[134:137], v[38:41]
	v_mfma_f32_16x16x32_bf16 v[234:237], v[174:177], v[142:145], v[34:37]
	s_setprio 0
	s_setprio 1
	v_mfma_f32_16x16x32_bf16 v[14:17], v[162:165], v[98:101], v[14:17]
	v_mfma_f32_16x16x32_bf16 v[10:13], v[162:165], v[114:117], v[10:13]
	v_mfma_f32_16x16x32_bf16 v[30:33], v[82:85], v[98:101], v[30:33]
	v_mfma_f32_16x16x32_bf16 v[26:29], v[82:85], v[114:117], v[26:29]
	v_mfma_f32_16x16x32_bf16 v[22:25], v[154:157], v[98:101], v[22:25]
	v_mfma_f32_16x16x32_bf16 v[18:21], v[154:157], v[114:117], v[18:21]
	v_mfma_f32_16x16x32_bf16 v[14:17], v[166:169], v[102:105], v[14:17]
	v_mfma_f32_16x16x32_bf16 v[10:13], v[166:169], v[222:225], v[10:13]
	v_mfma_f32_16x16x32_bf16 v[6:9], v[170:173], v[98:101], v[6:9]
	v_mfma_f32_16x16x32_bf16 v[2:5], v[170:173], v[114:117], v[2:5]
	v_mfma_f32_16x16x32_bf16 v[30:33], v[86:89], v[102:105], v[30:33]
	v_mfma_f32_16x16x32_bf16 v[26:29], v[86:89], v[222:225], v[26:29]
	v_mfma_f32_16x16x32_bf16 v[22:25], v[158:161], v[102:105], v[22:25]
	v_mfma_f32_16x16x32_bf16 v[18:21], v[158:161], v[222:225], v[18:21]
	v_mfma_f32_16x16x32_bf16 v[154:157], v[174:177], v[102:105], v[6:9]
	v_mfma_f32_16x16x32_bf16 v[158:161], v[174:177], v[222:225], v[2:5]
	s_setprio 0
	s_barrier
	s_nop 0
	ds_read_b128 v[2:5], v215
	ds_read_b128 v[6:9], v215 offset:1024
	ds_read_b128 v[162:165], v215 offset:2048
	ds_read_b128 v[166:169], v215 offset:3072
	ds_read_b128 v[34:37], v210 offset:32768
	ds_read_b128 v[38:41], v210 offset:33792
	ds_read_b128 v[50:53], v211 offset:32768
	ds_read_b128 v[170:173], v211 offset:33792
	ds_read_b128 v[174:177], v212 offset:32768
	ds_read_b128 v[222:225], v212 offset:33792
	ds_read_b128 v[238:241], v213 offset:32768
	ds_read_b128 v[242:245], v213 offset:33792
	s_waitcnt vmcnt(2)
	s_barrier
; #define LDA(dst, b, h) for (int m = 0; m < 4; ++m) for (int k = 0; k < 2; ++k) \
;     dst[m][k] = *reinterpret_cast<const bf16x8*>((char*)SA(b, h) + lds_byte(wr * 64 + m * 16 + fr, k * 32 + fq * 8))
; #define LDB(dst, b, h) for (int n = 0; n < 2; ++n) for (int k = 0; k < 2; ++k) \
;     dst[n][k] = *reinterpret_cast<const bf16x8*>((char*)SB(b, h) + lds_byte(wc * 32 + n * 16 + fr, k * 32 + fq * 8))
; #define MMA(ai, bj, At_, Bt_) do { __builtin_amdgcn_s_setprio(1); \
;     for (int m = 0; m < 4; ++m) for (int n = 0; n < 2; ++n) for (int k = 0; k < 2; ++k) \
;       acc[ai][bj][m][n] = __builtin_amdgcn_mfma_f32_16x16x32_bf16(At_[m][k], Bt_[n][k], acc[ai][bj][m][n], 0, 0, 0); \
;     __builtin_amdgcn_s_setprio(0); } while (0)
; #define WAIT_V(n) asm volatile("s_waitcnt vmcnt(" #n ")" ::: "memory")
; #define WAIT_L(n) asm volatile("s_waitcnt lgkmcnt(" #n ")" ::: "memory")
; #define BAR __builtin_amdgcn_s_barrier()
; __device__ __forceinline__ void gemm_kloop(const u16* __restrict__ A, const u16* __restrict__ Bt, const int K,
;                                            const int brow, const int bcol, f32x4 (&acc)[2][2][4][2], u16* shm, const int tidk,
;                                            const bool first) {
;     ...
;   { LDB(B0, 1, 0); LDA(At, 1, 0); WAIT_V(2); BAR; WAIT_L(0); MMA(0, 0, At, B0); BAR;
;     LDB(B1, 1, 1); WAIT_V(0); BAR; WAIT_L(0); MMA(0, 1, At, B1); BAR;
;     LDA(At, 1, 1); BAR; WAIT_L(0); MMA(1, 0, At, B0); MMA(1, 1, At, B1); BAR; }
;   if (wr == 0) BAR;
	s_waitcnt lgkmcnt(0)
	s_setprio 1
	s_waitcnt lgkmcnt(7)
	v_mfma_f32_16x16x32_bf16 v[82:85], v[34:37], v[2:5], v[126:129]
	s_waitcnt lgkmcnt(6)
	v_mfma_f32_16x16x32_bf16 v[130:133], v[38:41], v[6:9], v[82:85]
	v_mfma_f32_16x16x32_bf16 v[82:85], v[34:37], v[162:165], v[122:125]
	v_mfma_f32_16x16x32_bf16 v[134:137], v[38:41], v[166:169], v[82:85]
	s_waitcnt lgkmcnt(5)
	v_mfma_f32_16x16x32_bf16 v[82:85], v[50:53], v[2:5], v[118:121]
	s_waitcnt lgkmcnt(4)
	v_mfma_f32_16x16x32_bf16 v[114:117], v[170:173], v[6:9], v[82:85]
	v_mfma_f32_16x16x32_bf16 v[82:85], v[50:53], v[162:165], v[178:181]
	v_mfma_f32_16x16x32_bf16 v[118:121], v[170:173], v[166:169], v[82:85]
	s_waitcnt lgkmcnt(3)
	v_mfma_f32_16x16x32_bf16 v[82:85], v[174:177], v[2:5], v[110:113]
	s_waitcnt lgkmcnt(2)
	v_mfma_f32_16x16x32_bf16 v[98:101], v[222:225], v[6:9], v[82:85]
	v_mfma_f32_16x16x32_bf16 v[82:85], v[174:177], v[162:165], v[106:109]
	v_mfma_f32_16x16x32_bf16 v[102:105], v[222:225], v[166:169], v[82:85]
	s_waitcnt lgkmcnt(1)
	v_mfma_f32_16x16x32_bf16 v[82:85], v[238:241], v[2:5], v[182:185]
	v_mfma_f32_16x16x32_bf16 v[86:89], v[238:241], v[162:165], v[218:221]
	s_waitcnt lgkmcnt(0)
	v_mfma_f32_16x16x32_bf16 v[82:85], v[242:245], v[6:9], v[82:85]
	v_mfma_f32_16x16x32_bf16 v[86:89], v[242:245], v[166:169], v[86:89]
	s_setprio 0
	s_barrier
	ds_read_b128 v[178:181], v216
	ds_read_b128 v[182:185], v216 offset:1024
	ds_read_b128 v[218:221], v216 offset:2048
	ds_read_b128 v[246:249], v216 offset:3072
	s_waitcnt vmcnt(0)
	s_barrier
	s_waitcnt lgkmcnt(0)
	s_setprio 1
	s_waitcnt lgkmcnt(3)
	v_mfma_f32_16x16x32_bf16 v[94:97], v[34:37], v[178:181], v[94:97]
	s_waitcnt lgkmcnt(1)
	v_mfma_f32_16x16x32_bf16 v[34:37], v[34:37], v[218:221], v[90:93]
	s_waitcnt lgkmcnt(0)
	v_mfma_f32_16x16x32_bf16 v[142:145], v[38:41], v[246:249], v[34:37]
	v_mfma_f32_16x16x32_bf16 v[34:37], v[50:53], v[178:181], v[146:149]
	v_mfma_f32_16x16x32_bf16 v[122:125], v[170:173], v[182:185], v[34:37]
	v_mfma_f32_16x16x32_bf16 v[34:37], v[50:53], v[218:221], v[150:153]
	v_mfma_f32_16x16x32_bf16 v[126:129], v[170:173], v[246:249], v[34:37]
	v_mfma_f32_16x16x32_bf16 v[34:37], v[174:177], v[178:181], v[78:81]
	v_mfma_f32_16x16x32_bf16 v[106:109], v[222:225], v[182:185], v[34:37]
	v_mfma_f32_16x16x32_bf16 v[34:37], v[174:177], v[218:221], v[74:77]
	v_mfma_f32_16x16x32_bf16 v[110:113], v[222:225], v[246:249], v[34:37]
	v_mfma_f32_16x16x32_bf16 v[34:37], v[238:241], v[178:181], v[70:73]
	v_mfma_f32_16x16x32_bf16 v[90:93], v[242:245], v[182:185], v[34:37]
	v_mfma_f32_16x16x32_bf16 v[34:37], v[238:241], v[218:221], v[66:69]
	v_mfma_f32_16x16x32_bf16 v[138:141], v[38:41], v[182:185], v[94:97]
	v_mfma_f32_16x16x32_bf16 v[94:97], v[242:245], v[246:249], v[34:37]
	s_setprio 0
	s_barrier
	ds_read_b128 v[78:81], v210 offset:49152
	ds_read_b128 v[146:149], v210 offset:50176
	ds_read_b128 v[150:153], v211 offset:49152
	ds_read_b128 v[170:173], v211 offset:50176
	ds_read_b128 v[174:177], v212 offset:49152
	ds_read_b128 v[222:225], v212 offset:50176
	ds_read_b128 v[238:241], v213 offset:49152
	ds_read_b128 v[242:245], v213 offset:50176
	s_barrier
	s_waitcnt lgkmcnt(0)
	s_setprio 1
	s_waitcnt lgkmcnt(7)
	v_mfma_f32_16x16x32_bf16 v[34:37], v[78:81], v[2:5], v[62:65]
	s_waitcnt lgkmcnt(6)
	v_mfma_f32_16x16x32_bf16 v[66:69], v[146:149], v[6:9], v[34:37]
	v_mfma_f32_16x16x32_bf16 v[34:37], v[78:81], v[162:165], v[58:61]
	v_mfma_f32_16x16x32_bf16 v[70:73], v[146:149], v[166:169], v[34:37]
	s_waitcnt lgkmcnt(5)
	v_mfma_f32_16x16x32_bf16 v[34:37], v[150:153], v[2:5], v[54:57]
	s_waitcnt lgkmcnt(4)
	v_mfma_f32_16x16x32_bf16 v[50:53], v[170:173], v[6:9], v[34:37]
	v_mfma_f32_16x16x32_bf16 v[34:37], v[150:153], v[162:165], v[226:229]
	v_mfma_f32_16x16x32_bf16 v[54:57], v[170:173], v[166:169], v[34:37]
	s_waitcnt lgkmcnt(3)
	v_mfma_f32_16x16x32_bf16 v[34:37], v[174:177], v[2:5], v[46:49]
	s_waitcnt lgkmcnt(1)
	v_mfma_f32_16x16x32_bf16 v[2:5], v[238:241], v[2:5], v[230:233]
	v_mfma_f32_16x16x32_bf16 v[34:37], v[222:225], v[6:9], v[34:37]
	v_mfma_f32_16x16x32_bf16 v[38:41], v[174:177], v[162:165], v[42:45]
	s_waitcnt lgkmcnt(0)
	v_mfma_f32_16x16x32_bf16 v[2:5], v[242:245], v[6:9], v[2:5]
	v_mfma_f32_16x16x32_bf16 v[6:9], v[238:241], v[162:165], v[234:237]
	v_mfma_f32_16x16x32_bf16 v[38:41], v[222:225], v[166:169], v[38:41]
	v_mfma_f32_16x16x32_bf16 v[6:9], v[242:245], v[166:169], v[6:9]
	s_setprio 0
	s_setprio 1
	v_mfma_f32_16x16x32_bf16 v[14:17], v[174:177], v[178:181], v[14:17]
	v_mfma_f32_16x16x32_bf16 v[10:13], v[174:177], v[218:221], v[10:13]
	v_mfma_f32_16x16x32_bf16 v[30:33], v[78:81], v[178:181], v[30:33]
	v_mfma_f32_16x16x32_bf16 v[26:29], v[78:81], v[218:221], v[26:29]
	v_mfma_f32_16x16x32_bf16 v[22:25], v[150:153], v[178:181], v[22:25]
	v_mfma_f32_16x16x32_bf16 v[18:21], v[150:153], v[218:221], v[18:21]
	v_mfma_f32_16x16x32_bf16 v[42:45], v[222:225], v[182:185], v[14:17]
	v_mfma_f32_16x16x32_bf16 v[46:49], v[222:225], v[246:249], v[10:13]
	v_mfma_f32_16x16x32_bf16 v[10:13], v[238:241], v[178:181], v[154:157]
	v_mfma_f32_16x16x32_bf16 v[14:17], v[238:241], v[218:221], v[158:161]
	v_mfma_f32_16x16x32_bf16 v[74:77], v[146:149], v[182:185], v[30:33]
	v_mfma_f32_16x16x32_bf16 v[78:81], v[146:149], v[246:249], v[26:29]
	v_mfma_f32_16x16x32_bf16 v[58:61], v[170:173], v[182:185], v[22:25]
	v_mfma_f32_16x16x32_bf16 v[62:65], v[170:173], v[246:249], v[18:21]
	v_mfma_f32_16x16x32_bf16 v[10:13], v[242:245], v[182:185], v[10:13]
	v_mfma_f32_16x16x32_bf16 v[14:17], v[242:245], v[246:249], v[14:17]
	s_setprio 0
	v_readlane_b32 s0, v250, 51
	v_readlane_b32 s1, v250, 52
	s_barrier
	s_and_saveexec_b64 s[54:55], s[0:1]
	s_cbranch_execz .LBB0_156
	s_barrier
